# Wt_out and Wt_fi weight transposes moved from P0 into the P2 last-round hole (114 idle workgroups, hand-written pipelined transpose); pointers parked in v239
# speedup vs baseline: 1.0067x; 1.0041x over previous
; __global__ void __launch_bounds__(512, 2) mega_fwd(Args a) {
;     ...
;     unsigned char* ws = a.ws;
;     const float *x_p = a.in[0], *x_s = a.in[1], *cache_ckv = a.in[2], *cache_kr = a.in[3], *c_p = a.in[4], *c_s = a.in[5], *w_ada = a.in[6], *b_ada = a.in[7],
;                 *norm1_g = a.in[8], *w_in = a.in[9], *w_s = a.in[10], *b_s = a.in[11], *q_norm_g = a.in[12], *w_uq = a.in[13], *kv_norm_g = a.in[14], *w_ukv = a.in[15],
;                 *qn_g = a.in[16], *qr_g = a.in[17], *kn_g = a.in[18], *kr_g = a.in[19], *w_out = a.in[20], *norm2_g = a.in[21], *w_fi = a.in[22], *w_fo = a.in[23];
;     float* out = a.out;
;     float* PART = (float*)(ws + WS_PART); bf16_t* X1B = (bf16_t*)(ws + WS_X1B);
;     float* MOD = (float*)(ws + WS_MOD); float* ROPE = (float*)(ws + WS_ROPE); float* SSQ = (float*)(ws + WS_SSQ);
;     bf16_t *Wm = (bf16_t*)(ws + WS_WM), *Wt_in = (bf16_t*)(ws + WS_WIN), *Wt_uq = (bf16_t*)(ws + WS_WUQ), *Wt_ukv = (bf16_t*)(ws + WS_WUKV), *Wt_out = (bf16_t*)(ws + WS_WOUT),
;            *Wt_fi = (bf16_t*)(ws + WS_WFI), *Wt_fo = (bf16_t*)(ws + WS_WFO), *Hb = (bf16_t*)(ws + WS_H), *YAB = (bf16_t*)(ws + WS_YAB), *Gb = (bf16_t*)(ws + WS_G),
;            *Ub = (bf16_t*)(ws + WS_U), *Vt = (bf16_t*)(ws + WS_VT), *CQ = (bf16_t*)(ws + WS_CQ), *CKV = (bf16_t*)(ws + WS_CKV), *KR = (bf16_t*)(ws + WS_KR),
;            *KN = (bf16_t*)(ws + WS_KN), *VVt = (bf16_t*)(ws + WS_VVT), *Qb = (bf16_t*)(ws + WS_Q);
;     ...
;             if (r < I_ROPE) { const int e = r * 64 + lane, pos = e >> 4, j = e & 15;
;                 const double inv = exp(-(double)j * (1.0 / 16.0) * 9.210340371976184);
;                 const double rev = (double)pos * inv * 0.15915494309189535; const float fr = (float)(rev - floor(rev));
;                 ROPE[(size_t)pos * 32 + j] = __builtin_amdgcn_cosf(fr); ROPE[(size_t)pos * 32 + 16 + j] = __builtin_amdgcn_sinf(fr); continue; } r -= I_ROPE;
.LBB0_18:
	s_load_dwordx16 s[52:67], s[0:1], 0x40
	s_load_dwordx16 s[36:51], s[0:1], 0x80
	s_add_u32 s76, s30, 0x80000
	s_addc_u32 s77, s31, 0
	s_add_u32 s0, s30, 0x300000
	s_addc_u32 s1, s31, 0
	s_waitcnt lgkmcnt(0)
	v_writelane_b32 v239, s44, 0
	v_writelane_b32 v239, s45, 1
	v_writelane_b32 v239, s48, 2
	v_writelane_b32 v239, s49, 3
	v_writelane_b32 v239, s50, 4
	v_writelane_b32 v239, s51, 5
	v_writelane_b32 v238, s36, 20
	s_add_u32 s8, s30, 0x400000
	s_addc_u32 s9, s31, 0
	v_writelane_b32 v238, s37, 21
	v_writelane_b32 v238, s38, 22
	v_writelane_b32 v238, s39, 23
	v_writelane_b32 v238, s40, 24
	v_writelane_b32 v238, s41, 25
	v_writelane_b32 v238, s42, 26
	v_writelane_b32 v238, s43, 27
	v_writelane_b32 v238, s44, 28
	v_writelane_b32 v238, s45, 29
	v_writelane_b32 v238, s46, 30
	v_writelane_b32 v238, s47, 31
	v_writelane_b32 v238, s48, 32
	v_writelane_b32 v238, s49, 33
	v_writelane_b32 v238, s50, 34
	v_writelane_b32 v238, s51, 35
	v_writelane_b32 v238, s0, 36
	s_nop 1
	v_writelane_b32 v238, s1, 37
	s_add_u32 s0, s30, 0x800000
	s_addc_u32 s1, s31, 0
	s_add_u32 s68, s30, 0x900000
	v_writelane_b32 v238, s0, 38
	s_addc_u32 s69, s31, 0
	s_nop 0
	v_writelane_b32 v238, s1, 39
	s_add_u32 s0, s30, 0xa00000
	s_addc_u32 s1, s31, 0
	v_writelane_b32 v238, s0, 40
	s_nop 1
	v_writelane_b32 v238, s1, 41
	s_add_u32 s0, s30, 0xc00000
	s_addc_u32 s1, s31, 0
	v_writelane_b32 v238, s0, 42
	s_nop 1
	v_writelane_b32 v238, s1, 43
	s_add_u32 s0, s30, 0x1700000
	s_addc_u32 s1, s31, 0
	s_add_u32 s74, s30, 0xfa00000
	s_addc_u32 s75, s31, 0
	s_add_u32 s14, s30, 0x11300000
	s_addc_u32 s15, s31, 0
	s_lshl_b32 s6, s2, 3
	s_add_i32 s3, s6, 0xfffffd00
	v_writelane_b32 v238, s0, 44
	s_cmpk_gt_i32 s34, 0x80
	s_nop 0
	v_writelane_b32 v238, s1, 45
	s_cselect_b64 s[0:1], -1, 0
	s_and_b64 s[4:5], s[0:1], exec
	s_cselect_b32 s3, s3, s6
	s_and_b64 s[4:5], s[82:83], s[0:1]
	s_add_i32 s3, s7, s3
	s_and_b64 s[4:5], s[4:5], exec
	s_cselect_b32 s4, 0x7fffffff, s3
	s_lshl_b32 s12, s34, 3
	s_cmpk_gt_i32 s4, 0x370f
	v_writelane_b32 v238, s6, 46
	s_cbranch_scc1 .LBB0_174
	s_add_i32 s5, s12, 0xfffffd00
	s_and_b64 s[0:1], s[0:1], exec
	v_and_b32_e32 v12, 15, v174
	v_cvt_f64_u32_e32 v[2:3], v12
	s_mov_b32 s0, 0xbbb55516
	v_ldexp_f64 v[2:3], -v[2:3], -4
	s_mov_b32 s1, 0x40226bb1
	v_mul_f64 v[2:3], v[2:3], s[0:1]
	s_mov_b32 s0, 0x652b82fe
	s_mov_b32 s1, 0x3ff71547
	v_mul_f64 v[4:5], v[2:3], s[0:1]
	s_mov_b32 s0, 0xfefa39ef
	v_rndne_f64_e32 v[4:5], v[4:5]
	s_mov_b32 s1, 0xbfe62e42
	v_fma_f64 v[6:7], s[0:1], v[4:5], v[2:3]
	s_mov_b32 s0, 0x3b39803f
	s_mov_b32 s1, 0xbc7abc9e
	v_fmac_f64_e32 v[6:7], s[0:1], v[4:5]
	s_mov_b32 s0, 0x6a5dcb37
	v_mov_b32_e32 v8, 0xfca7ab0c
	v_mov_b32_e32 v9, 0x3e928af3
	s_mov_b32 s1, 0x3e5ade15
	v_fmac_f64_e32 v[8:9], s[0:1], v[6:7]
	v_mov_b32_e32 v10, 0x623fde64
	v_mov_b32_e32 v11, 0x3ec71dee
	v_fmac_f64_e32 v[10:11], v[6:7], v[8:9]
	v_mov_b32_e32 v8, 0x7c89e6b0
	v_mov_b32_e32 v9, 0x3efa0199
	v_fmac_f64_e32 v[8:9], v[6:7], v[10:11]
	v_mov_b32_e32 v10, 0x14761f6e
	v_mov_b32_e32 v11, 0x3f2a01a0
	v_fmac_f64_e32 v[10:11], v[6:7], v[8:9]
	v_mov_b32_e32 v8, 0x1852b7b0
	v_mov_b32_e32 v9, 0x3f56c16c
	v_fmac_f64_e32 v[8:9], v[6:7], v[10:11]
	v_mov_b32_e32 v10, 0x11122322
	v_mov_b32_e32 v11, 0x3f811111
	v_fmac_f64_e32 v[10:11], v[6:7], v[8:9]
	v_mov_b32_e32 v8, 0x555502a1
	v_mov_b32_e32 v9, 0x3fa55555
	v_fmac_f64_e32 v[8:9], v[6:7], v[10:11]
	v_mov_b32_e32 v10, 0x55555511
	v_mov_b32_e32 v11, 0x3fc55555
	v_fmac_f64_e32 v[10:11], v[6:7], v[8:9]
	v_mov_b32_e32 v8, 11
	v_mov_b32_e32 v9, 0x3fe00000
	v_fmac_f64_e32 v[8:9], v[6:7], v[10:11]
	s_mov_b32 s0, 0
	v_fma_f64 v[8:9], v[6:7], v[8:9], 1.0
	s_mov_b32 s1, 0x40900000
	v_fma_f64 v[6:7], v[6:7], v[8:9], 1.0
	v_cvt_i32_f64_e32 v4, v[4:5]
	v_cmp_nlt_f64_e32 vcc, s[0:1], v[2:3]
	s_mov_b32 s0, 0
	v_ldexp_f64 v[4:5], v[6:7], v4
	v_mov_b32_e32 v6, 0x7ff00000
	s_mov_b32 s1, 0xc090cc00
	v_cndmask_b32_e32 v5, v6, v5, vcc
	v_cmp_ngt_f64_e64 s[0:1], s[0:1], v[2:3]
	s_cselect_b32 s6, s5, s12
	s_and_b64 vcc, s[0:1], vcc
	v_cndmask_b32_e64 v3, 0, v5, s[0:1]
	v_lshrrev_b32_e32 v43, 5, v1
	s_movk_i32 s0, 0x84
	v_mov_b32_e32 v18, 0x108
	v_mad_u32_u24 v28, v43, s0, v18
	v_mov_b32_e32 v18, 0x210
	v_mad_u32_u24 v48, v43, s0, v18
	v_mov_b32_e32 v18, 0x318
	v_mad_u32_u24 v29, v43, s0, v18
	v_mov_b32_e32 v18, 0x420
	v_mad_u32_u24 v51, v43, s0, v18
	v_mov_b32_e32 v18, 0x528
	v_mad_u32_u24 v30, v43, s0, v18
	v_mov_b32_e32 v18, 0x630
	v_mad_u32_u24 v52, v43, s0, v18
	v_mov_b32_e32 v18, 0x738
	v_mad_u32_u24 v31, v43, s0, v18
	v_mov_b32_e32 v18, 0x840
	v_mad_u32_u24 v53, v43, s0, v18
	v_mov_b32_e32 v18, 0x948
	v_mad_u32_u24 v32, v43, s0, v18
	v_mov_b32_e32 v18, 0xa50
	v_mad_u32_u24 v54, v43, s0, v18
	v_mov_b32_e32 v18, 0xb58
	v_mad_u32_u24 v33, v43, s0, v18
	v_mov_b32_e32 v18, 0xc60
	v_mad_u32_u24 v55, v43, s0, v18
	v_mov_b32_e32 v18, 0xd68
	v_mad_u32_u24 v34, v43, s0, v18
	v_mov_b32_e32 v18, 0xe70
	v_mad_u32_u24 v56, v43, s0, v18
	v_mov_b32_e32 v18, 0xf78
	v_mad_u32_u24 v35, v43, s0, v18
	v_mov_b32_e32 v18, 0x1080
	v_mad_u32_u24 v57, v43, s0, v18
; __device__ __forceinline__ void p0_transpose_item(const float* W, int ldw, int c0, int k0, bf16_t* WT, int K, int n0, const float* kscale, LAS float* scr, int lane) {
; #pragma unroll
;     for (int i = 0; i < 32; ++i) { const int kk = 2 * i + (lane >> 5); float v = 0.f;
;         if (c0 >= 0) v = __builtin_nontemporal_load(W + (size_t)(k0 + kk) * ldw + c0 + (lane & 31));
;         if (kscale) v *= kscale[k0 + kk];
;         scr[kk * 33 + (lane & 31)] = v; }
;     LDS_WAIT(); asm volatile("" ::: "memory");
;     const int c = lane & 7;
; #pragma unroll
;     for (int j = 0; j < 4; ++j) { const int n = (lane >> 3) + 8 * j; const LAS float* s = scr + (8 * c) * 33 + n;
;         u32x4 o; o.x = cvt_pk_bf16(s[0 * 33], s[1 * 33]); o.y = cvt_pk_bf16(s[2 * 33], s[3 * 33]); o.z = cvt_pk_bf16(s[4 * 33], s[5 * 33]); o.w = cvt_pk_bf16(s[6 * 33], s[7 * 33]);
;         *(u32x4*)(WT + (size_t)(n0 + n) * K + k0 + 8 * c) = o; }
; __global__ void __launch_bounds__(512, 2) mega_fwd(Args a) {
;     ...
;         for (int it = gw; it < NITEMS; it += NGW) {
;             int r = it;
;             if (r < I_IN) { const int kb = r / 56, nb = r % 56, n0 = nb * 32;
;                 const int c0 = n0 < 512 ? n0 : n0 < 768 ? 1408 + (n0 - 512) : n0 < 1152 ? 1024 + (n0 - 768) : n0 < 1184 ? 1664 : n0 < 1280 ? -1 : 512 + (n0 - 1280);
;                 p0_transpose_item(w_in, 1696, c0, kb * 64, Wt_in, 1024, n0, nullptr, scr, lane); continue; } r -= I_IN;
;             if (r < I_UQ) { const int kb = r / 24, nb = r % 24, pn = nb >> 3, bj = (nb >> 2) & 1, wc = nb & 3;
;                 const int c0 = pn < 2 ? 96 * (4 * pn + wc) + 32 * bj : 96 * (4 * bj + wc) + 64;
;                 p0_transpose_item(w_uq, 768, c0, kb * 64, Wt_uq, 384, nb * 32, q_norm_g, scr, lane); continue; } r -= I_UQ;
;             if (r < I_UKV) { const int kb = r / 32, nb = r % 32; int c0;
;                 if (nb < 16) { const int pn = nb >> 3, bj = (nb >> 2) & 1, wc = nb & 3; c0 = 128 * (4 * pn + wc) + 32 * bj; }
;                 else { const int ch0 = (nb - 16) * 32; c0 = 128 * (ch0 >> 6) + 64 + (ch0 & 63); }
;                 p0_transpose_item(w_ukv, 1024, c0, kb * 64, Wt_ukv, 256, nb * 32, nullptr, scr, lane); continue; } r -= I_UKV;
;             if (r < I_OUT) { const int kb = r / 32, nb = r % 32; p0_transpose_item(w_out, 1024, nb * 32, kb * 64, Wt_out, 1024, nb * 32, nullptr, scr, lane); continue; } r -= I_OUT;
	v_mov_b32_e32 v18, 0x1188
	v_mad_u32_u24 v36, v43, s0, v18
	v_mov_b32_e32 v18, 0x1290
	v_mad_u32_u24 v58, v43, s0, v18
	v_mov_b32_e32 v18, 0x1398
	v_mad_u32_u24 v37, v43, s0, v18
	v_mov_b32_e32 v18, 0x14a0
	v_mad_u32_u24 v59, v43, s0, v18
	v_mov_b32_e32 v18, 0x15a8
	s_lshl_b32 s7, s7, 14
	v_readlane_b32 s36, v238, 4
	v_mad_u32_u24 v38, v43, s0, v18
	v_mov_b32_e32 v18, 0x16b0
	s_add_i32 s7, s7, 0
	v_readlane_b32 s37, v238, 5
	v_mad_u32_u24 v60, v43, s0, v18
	v_mov_b32_e32 v18, 0x17b8
	v_cndmask_b32_e32 v2, 0, v4, vcc
	v_lshlrev_b32_e32 v4, 2, v12
	v_mov_b32_e32 v5, 0
	v_and_b32_e32 v10, 7, v174
	v_readlane_b32 s38, v238, 6
	v_readlane_b32 s39, v238, 7
	v_readlane_b32 s40, v238, 8
	v_readlane_b32 s41, v238, 9
	v_readlane_b32 s42, v238, 10
	v_readlane_b32 s43, v238, 11
	s_mov_b64 s[16:17], s[36:37]
	v_mad_u32_u24 v39, v43, s0, v18
	v_mov_b32_e32 v18, 0x18c0
	s_cmp_lg_u64 s[60:61], 0
	v_lshl_add_u64 v[6:7], s[76:77], 0, v[4:5]
	v_lshlrev_b32_e32 v4, 4, v10
	s_mov_b64 s[22:23], s[42:43]
	v_mad_u32_u24 v61, v43, s0, v18
	s_cselect_b64 s[16:17], -1, 0
	s_lshl_b32 s0, s3, 6
	v_readlane_b32 s44, v238, 12
	v_readlane_b32 s45, v238, 13
	v_readlane_b32 s46, v238, 14
	v_readlane_b32 s47, v238, 15
	v_readlane_b32 s48, v238, 16
	v_readlane_b32 s49, v238, 17
	v_readlane_b32 s50, v238, 18
	v_readlane_b32 s51, v238, 19
	v_lshl_add_u64 v[8:9], s[22:23], 0, v[4:5]
	v_lshlrev_b32_e32 v4, 3, v10
	s_add_i32 s24, s0, 0xfff33c00
	s_lshl_b32 s0, s3, 3
	s_mov_b64 s[18:19], s[38:39]
	s_mov_b64 s[20:21], s[40:41]
	v_lshl_add_u64 v[10:11], s[14:15], 0, v[4:5]
	v_lshlrev_b32_e32 v4, 4, v1
	v_lshlrev_b32_e32 v16, 2, v174
	v_readlane_b32 s36, v238, 20
	s_add_i32 s26, s0, 0xfffec780
	s_lshl_b32 s0, s3, 2
	v_lshl_add_u64 v[12:13], s[20:21], 0, v[4:5]
	v_lshlrev_b32_e32 v4, 3, v1
	v_and_b32_e32 v26, 0x7c, v16
	v_mov_b32_e32 v27, v5
	v_readlane_b32 s50, v238, 34
	v_readlane_b32 s51, v238, 35
	s_add_i32 s18, s0, 0xffffa3c0
	s_lshl_b32 s0, s3, 1
	v_lshl_add_u64 v[14:15], s[74:75], 0, v[4:5]
	v_lshl_add_u64 v[16:17], s[50:51], 0, v[26:27]
	v_and_b32_e32 v4, 56, v4
	s_add_i32 s50, s0, 0xffffdce0
	v_readlane_b32 s0, v238, 44
	v_add_u32_e32 v44, s7, v26
	v_mul_u32_u24_e32 v18, 0x84, v4
	v_lshlrev_b32_e32 v4, 1, v4
	v_readlane_b32 s1, v238, 45
	v_add_u32_e32 v76, v44, v28
	v_add_u32_e32 v77, v44, v29
	v_lshl_add_u64 v[28:29], s[0:1], 0, v[4:5]
	v_readlane_b32 s0, v238, 42
	v_readlane_b32 s1, v238, 43
	v_add_u32_e32 v78, v44, v30
	v_add_u32_e32 v79, v44, v31
	v_lshl_add_u64 v[30:31], s[0:1], 0, v[4:5]
	v_readlane_b32 s0, v238, 40
	v_readlane_b32 s1, v238, 41
	v_lshrrev_b32_e32 v42, 3, v1
	v_readlane_b32 s44, v238, 28
	v_readlane_b32 s45, v238, 29
	v_add_u32_e32 v80, v44, v32
	v_add_u32_e32 v81, v44, v33
	v_lshl_add_u64 v[32:33], s[0:1], 0, v[4:5]
	v_readlane_b32 s0, v238, 38
	v_readlane_b32 s48, v238, 32
	v_readlane_b32 s49, v238, 33
	v_lshlrev_b32_e32 v19, 2, v42
	v_lshl_add_u64 v[20:21], s[44:45], 0, v[26:27]
	s_mov_b32 s44, 0x6dc9c883
	v_readlane_b32 s1, v238, 39
	s_mov_b32 s5, 0
	v_mul_u32_u24_e32 v45, 0x84, v43
	v_or_b32_e32 v46, 2, v43
	v_or_b32_e32 v47, 4, v43
	v_or_b32_e32 v49, 6, v43
	v_or_b32_e32 v50, 8, v43
	v_add3_u32 v62, s7, v18, v19
	v_lshl_add_u64 v[18:19], s[48:49], 0, v[26:27]
	v_lshl_add_u64 v[22:23], s[66:67], 0, v[26:27]
	v_lshl_add_u64 v[24:25], s[62:63], 0, v[26:27]
	v_lshl_add_u64 v[26:27], s[54:55], 0, v[26:27]
	s_and_b32 s7, s4, 3
	s_and_b32 s21, s4, 1
	v_or_b32_e32 v63, 10, v43
	s_lshl_b32 s22, s3, 5
	v_or_b32_e32 v64, 12, v43
	s_lshl_b32 s23, s6, 5
	v_or_b32_e32 v65, 14, v43
	v_or_b32_e32 v66, 16, v43
	s_lshl_b32 s25, s6, 6
	v_or_b32_e32 v67, 18, v43
	v_or_b32_e32 v68, 20, v43
	s_lshl_b32 s27, s6, 3
	v_or_b32_e32 v69, 22, v43
	v_or_b32_e32 v70, 24, v43
	v_or_b32_e32 v71, 26, v43
	s_lshl_b32 s33, s6, 2
	v_or_b32_e32 v72, 28, v43
	v_or_b32_e32 v73, 30, v43
	s_lshl_b32 s51, s6, 1
	v_or_b32_e32 v74, 32, v43
	v_or_b32_e32 v75, 34, v43
	s_mov_b32 s45, 0x3fc45f30
	v_add_u32_e32 v82, v44, v34
	v_add_u32_e32 v83, v44, v35
	v_add_u32_e32 v84, v44, v36
	v_add_u32_e32 v85, v44, v37
	v_add_u32_e32 v86, v44, v38
	v_add_u32_e32 v87, v44, v39
	v_or_b32_e32 v88, 36, v43
	s_movk_i32 s54, 0x1a80
	v_or_b32_e32 v89, 38, v43
	v_or_b32_e32 v90, 40, v43
	v_or_b32_e32 v91, 42, v43
	v_or_b32_e32 v92, 44, v43
	v_or_b32_e32 v93, 46, v43
	v_or_b32_e32 v94, 48, v43
	v_or_b32_e32 v95, 50, v43
	v_or_b32_e32 v96, 52, v43
	v_or_b32_e32 v97, 54, v43
	v_or_b32_e32 v98, 56, v43
	v_or_b32_e32 v99, 58, v43
	v_or_b32_e32 v100, 60, v43
	v_or_b32_e32 v101, 62, v43
	v_or_b32_e32 v102, 8, v42
	v_or_b32_e32 v103, 16, v42
	v_or_b32_e32 v104, 24, v42
	v_lshl_add_u64 v[34:35], s[68:69], 0, v[4:5]
	v_lshl_add_u64 v[36:37], s[0:1], 0, v[4:5]
	v_lshl_add_u64 v[38:39], s[8:9], 0, v[4:5]
	v_readlane_b32 s37, v238, 21
	v_readlane_b32 s38, v238, 22
	v_readlane_b32 s39, v238, 23
	v_readlane_b32 s40, v238, 24
	v_readlane_b32 s41, v238, 25
	v_readlane_b32 s42, v238, 26
	v_readlane_b32 s43, v238, 27
	v_readlane_b32 s46, v238, 30
	v_readlane_b32 s47, v238, 31
	s_branch .LBB0_22

; __global__ void __launch_bounds__(512, 2) mega_fwd(Args a) {
;     ...
;         for (int it = gw; it < NITEMS; it += NGW) {
;             int r = it;
;             if (r < I_IN) { const int kb = r / 56, nb = r % 56, n0 = nb * 32;
;                 const int c0 = n0 < 512 ? n0 : n0 < 768 ? 1408 + (n0 - 512) : n0 < 1152 ? 1024 + (n0 - 768) : n0 < 1184 ? 1664 : n0 < 1280 ? -1 : 512 + (n0 - 1280);
;                 p0_transpose_item(w_in, 1696, c0, kb * 64, Wt_in, 1024, n0, nullptr, scr, lane); continue; } r -= I_IN;
;             if (r < I_UQ) { const int kb = r / 24, nb = r % 24, pn = nb >> 3, bj = (nb >> 2) & 1, wc = nb & 3;
;                 const int c0 = pn < 2 ? 96 * (4 * pn + wc) + 32 * bj : 96 * (4 * bj + wc) + 64;
;                 p0_transpose_item(w_uq, 768, c0, kb * 64, Wt_uq, 384, nb * 32, q_norm_g, scr, lane); continue; } r -= I_UQ;
;             if (r < I_UKV) { const int kb = r / 32, nb = r % 32; int c0;
;                 if (nb < 16) { const int pn = nb >> 3, bj = (nb >> 2) & 1, wc = nb & 3; c0 = 128 * (4 * pn + wc) + 32 * bj; }
;                 else { const int ch0 = (nb - 16) * 32; c0 = 128 * (ch0 >> 6) + 64 + (ch0 & 63); }
;                 p0_transpose_item(w_ukv, 1024, c0, kb * 64, Wt_ukv, 256, nb * 32, nullptr, scr, lane); continue; } r -= I_UKV;
;             if (r < I_OUT) { const int kb = r / 32, nb = r % 32; p0_transpose_item(w_out, 1024, nb * 32, kb * 64, Wt_out, 1024, nb * 32, nullptr, scr, lane); continue; } r -= I_OUT;
;             if (r < I_FI) { const int kb = r / 176, nb = r % 176, n0 = nb * 32, pn = n0 >> 8, bj = (n0 >> 7) & 1, rr = n0 & 127;
;                 p0_transpose_item(w_fi, 5632, bj * 2816 + 128 * pn + rr, kb * 64, Wt_fi, 1024, n0, nullptr, scr, lane); continue; } r -= I_FI;
;             if (r < I_FO) { const int kb = r / 32, nb = r % 32; p0_transpose_item(w_fo, 1024, nb * 32, kb * 64, Wt_fo, 2816, nb * 32, nullptr, scr, lane); continue; } r -= I_FO;
.LBB0_22:
	s_cmpk_lt_u32 s3, 0x490
	s_cbranch_scc1 .Lp0_keep
	s_cmpk_lt_u32 s3, 0x1190
	s_cbranch_scc1 .LBB0_21

; #define LAS __attribute__((address_space(3)))
; __device__ __forceinline__ unsigned cvt_pk_bf16(float lo, float hi) { unsigned r; asm("v_cvt_pk_bf16_f32 %0, %1, %2" : "=v"(r) : "v"(lo), "v"(hi)); return r; }
; #define LDS_WAIT() asm volatile("s_waitcnt lgkmcnt(0)" ::: "memory")
; __device__ __forceinline__ void p0_transpose_item(const float* W, int ldw, int c0, int k0, bf16_t* WT, int K, int n0, const float* kscale, LAS float* scr, int lane) {
; #pragma unroll
;     for (int i = 0; i < 32; ++i) { const int kk = 2 * i + (lane >> 5); float v = 0.f;
;         if (c0 >= 0) v = __builtin_nontemporal_load(W + (size_t)(k0 + kk) * ldw + c0 + (lane & 31));
;         if (kscale) v *= kscale[k0 + kk];
;         scr[kk * 33 + (lane & 31)] = v; }
;     LDS_WAIT(); asm volatile("" ::: "memory");
;     const int c = lane & 7;
; #pragma unroll
;     for (int j = 0; j < 4; ++j) { const int n = (lane >> 3) + 8 * j; const LAS float* s = scr + (8 * c) * 33 + n;
;         u32x4 o; o.x = cvt_pk_bf16(s[0 * 33], s[1 * 33]); o.y = cvt_pk_bf16(s[2 * 33], s[3 * 33]); o.z = cvt_pk_bf16(s[4 * 33], s[5 * 33]); o.w = cvt_pk_bf16(s[6 * 33], s[7 * 33]);
;         *(u32x4*)(WT + (size_t)(n0 + n) * K + k0 + 8 * c) = o; }
; __global__ void __launch_bounds__(512, 2) mega_fwd(Args a) {
;     ...
;             if (r < I_OUT) { const int kb = r / 32, nb = r % 32; p0_transpose_item(w_out, 1024, nb * 32, kb * 64, Wt_out, 1024, nb * 32, nullptr, scr, lane); continue; } r -= I_OUT;
;             if (r < I_FI) { const int kb = r / 176, nb = r % 176, n0 = nb * 32, pn = n0 >> 8, bj = (n0 >> 7) & 1, rr = n0 & 127;
;                 p0_transpose_item(w_fi, 5632, bj * 2816 + 128 * pn + rr, kb * 64, Wt_fi, 1024, n0, nullptr, scr, lane); continue; } r -= I_FI;
;             if (r < I_FO) { const int kb = r / 32, nb = r % 32; p0_transpose_item(w_fo, 1024, nb * 32, kb * 64, Wt_fo, 2816, nb * 32, nullptr, scr, lane); continue; } r -= I_FO;
.LBB0_488:
	s_cmpk_lt_i32 s2, 0x8e
	s_cbranch_scc1 .Lht_skip
	v_writelane_b32 v239, s0, 8
	v_writelane_b32 v239, s1, 9
	v_writelane_b32 v239, s3, 10
	v_writelane_b32 v239, s4, 11
	v_writelane_b32 v239, s5, 12
	v_writelane_b32 v239, s6, 13
	v_writelane_b32 v239, s7, 14
	v_writelane_b32 v239, s8, 15
	v_writelane_b32 v239, s9, 16
	v_writelane_b32 v239, s10, 17
	v_writelane_b32 v239, s11, 18
	v_writelane_b32 v239, s21, 19
	v_writelane_b32 v239, s22, 20
	v_writelane_b32 v239, s23, 21
	v_writelane_b32 v239, s24, 22
	v_writelane_b32 v239, s25, 23
	v_writelane_b32 v239, s40, 24
	v_writelane_b32 v239, s41, 25
	v_writelane_b32 v239, s42, 26
	v_writelane_b32 v239, s43, 27
	v_writelane_b32 v239, vcc_lo, 30
	v_writelane_b32 v239, vcc_hi, 31
	v_readfirstlane_b32 s21, v211
	s_ashr_i32 s21, s21, 6
	s_add_i32 s3, s2, 0xffffff72
	s_lshl_b32 s3, s3, 3
	s_add_i32 s3, s3, s21
	s_lshl_b32 s21, s21, 14
	v_and_b32_e32 v0, 63, v211
	v_lshrrev_b32_e32 v1, 5, v0
	v_and_b32_e32 v2, 31, v0
	v_and_b32_e32 v3, 7, v0
	v_lshrrev_b32_e32 v4, 3, v0
	v_mul_u32_u24_e32 v5, 33, v1
	v_add_lshl_u32 v5, v5, v2, 2
	v_add_u32_e32 v5, s21, v5
	v_mul_u32_u24_e32 v8, 0x108, v3
	v_add_lshl_u32 v8, v8, v4, 2
	v_add_u32_e32 v8, s21, v8
	s_cmpk_lt_u32 s3, 0x200
	s_cbranch_scc0 .Lht1_not_out
	s_lshr_b32 s22, s3, 5
	s_and_b32 s23, s3, 31
	s_lshl_b32 s23, s23, 5
	s_mov_b32 s8, s23
	v_readlane_b32 s4, v239, 0
	v_readlane_b32 s5, v239, 1
	s_movk_i32 s25, 0x400
	s_movk_i32 s9, 0x400
	s_mov_b32 s0, 0xa00000
	s_branch .Lht1_go
.Lht1_not_out:
	s_cmpk_lt_u32 s3, 0xd00
	s_cbranch_scc0 .Lht1_fo
	s_add_i32 s0, s3, 0xfffffe00
	s_mul_i32 s22, s0, 0xba3
	s_lshr_b32 s22, s22, 19
	s_mul_i32 s1, s22, 0xb0
	s_sub_i32 s1, s0, s1
	s_lshl_b32 s23, s1, 5
	s_lshr_b32 s0, s23, 8
	s_lshl_b32 s0, s0, 7
	s_bfe_u32 s1, s23, 0x10007
	s_mul_i32 s1, s1, 0xb00
	s_and_b32 s8, s23, 0x7f
	s_add_i32 s8, s8, s0
	s_add_i32 s8, s8, s1
	v_readlane_b32 s4, v239, 2
	v_readlane_b32 s5, v239, 3
	s_movk_i32 s25, 0x1600
	s_movk_i32 s9, 0x400
	s_mov_b32 s0, 0xc00000
	s_branch .Lht1_go
.Lht1_fo:
	s_add_i32 s0, s3, 0xfffff300
	s_lshr_b32 s22, s0, 5
	s_and_b32 s23, s0, 31
	s_lshl_b32 s23, s23, 5
	s_mov_b32 s8, s23
	v_readlane_b32 s4, v239, 4
	v_readlane_b32 s5, v239, 5
	s_movk_i32 s25, 0x400
	s_movk_i32 s9, 0xb00
	s_mov_b32 s0, 0x1700000
.Lht1_go:
	s_add_u32 s10, s30, s0
	s_addc_u32 s11, s31, 0
	s_lshl_b32 s24, s9, 4
	s_lshl_b32 s7, s22, 6
	s_mul_i32 s0, s7, s25
	s_add_i32 s0, s0, s8
	s_lshl_b32 s0, s0, 2
	s_add_u32 s4, s4, s0
	s_addc_u32 s5, s5, 0
	s_lshl_b32 s6, s25, 3
	v_mul_u32_u24_e32 v9, s25, v1
	v_add_lshl_u32 v9, v9, v2, 2
	global_load_dword v10, v9, s[4:5] nt
	s_add_u32 s4, s4, s6
	s_addc_u32 s5, s5, 0
	global_load_dword v11, v9, s[4:5] nt
	s_add_u32 s4, s4, s6
	s_addc_u32 s5, s5, 0
	global_load_dword v12, v9, s[4:5] nt
	s_add_u32 s4, s4, s6
	s_addc_u32 s5, s5, 0
	global_load_dword v13, v9, s[4:5] nt
	s_add_u32 s4, s4, s6
	s_addc_u32 s5, s5, 0
	global_load_dword v14, v9, s[4:5] nt
	s_add_u32 s4, s4, s6
	s_addc_u32 s5, s5, 0
	global_load_dword v15, v9, s[4:5] nt
	s_add_u32 s4, s4, s6
	s_addc_u32 s5, s5, 0
	global_load_dword v16, v9, s[4:5] nt
	s_add_u32 s4, s4, s6
	s_addc_u32 s5, s5, 0
	global_load_dword v17, v9, s[4:5] nt
	s_add_u32 s4, s4, s6
	s_addc_u32 s5, s5, 0
	global_load_dword v18, v9, s[4:5] nt
	s_add_u32 s4, s4, s6
	s_addc_u32 s5, s5, 0
	global_load_dword v19, v9, s[4:5] nt
	s_add_u32 s4, s4, s6
	s_addc_u32 s5, s5, 0
	global_load_dword v20, v9, s[4:5] nt
	s_add_u32 s4, s4, s6
	s_addc_u32 s5, s5, 0
	global_load_dword v21, v9, s[4:5] nt
	s_add_u32 s4, s4, s6
	s_addc_u32 s5, s5, 0
	global_load_dword v22, v9, s[4:5] nt
	s_add_u32 s4, s4, s6
	s_addc_u32 s5, s5, 0
	global_load_dword v23, v9, s[4:5] nt
	s_add_u32 s4, s4, s6
	s_addc_u32 s5, s5, 0
	global_load_dword v24, v9, s[4:5] nt
	s_add_u32 s4, s4, s6
	s_addc_u32 s5, s5, 0
	global_load_dword v25, v9, s[4:5] nt
	s_add_u32 s4, s4, s6
	s_addc_u32 s5, s5, 0
	global_load_dword v26, v9, s[4:5] nt
	s_add_u32 s4, s4, s6
	s_addc_u32 s5, s5, 0
	global_load_dword v27, v9, s[4:5] nt
	s_add_u32 s4, s4, s6
	s_addc_u32 s5, s5, 0
	global_load_dword v28, v9, s[4:5] nt
	s_add_u32 s4, s4, s6
	s_addc_u32 s5, s5, 0
	global_load_dword v29, v9, s[4:5] nt
	s_add_u32 s4, s4, s6
	s_addc_u32 s5, s5, 0
	global_load_dword v30, v9, s[4:5] nt
	s_add_u32 s4, s4, s6
	s_addc_u32 s5, s5, 0
	global_load_dword v31, v9, s[4:5] nt
	s_add_u32 s4, s4, s6
	s_addc_u32 s5, s5, 0
	global_load_dword v32, v9, s[4:5] nt
	s_add_u32 s4, s4, s6
	s_addc_u32 s5, s5, 0
	global_load_dword v33, v9, s[4:5] nt
	s_add_u32 s4, s4, s6
	s_addc_u32 s5, s5, 0
	global_load_dword v34, v9, s[4:5] nt
	s_add_u32 s4, s4, s6
	s_addc_u32 s5, s5, 0
	global_load_dword v35, v9, s[4:5] nt
	s_add_u32 s4, s4, s6
	s_addc_u32 s5, s5, 0
	global_load_dword v36, v9, s[4:5] nt
	s_add_u32 s4, s4, s6
	s_addc_u32 s5, s5, 0
	global_load_dword v37, v9, s[4:5] nt
	s_add_u32 s4, s4, s6
	s_addc_u32 s5, s5, 0
	global_load_dword v38, v9, s[4:5] nt
	s_add_u32 s4, s4, s6
	s_addc_u32 s5, s5, 0
	global_load_dword v39, v9, s[4:5] nt
	s_add_u32 s4, s4, s6
	s_addc_u32 s5, s5, 0
	global_load_dword v40, v9, s[4:5] nt
	s_add_u32 s4, s4, s6
	s_addc_u32 s5, s5, 0
	global_load_dword v41, v9, s[4:5] nt
	v_add_u32_e32 v62, s23, v4
	v_mul_u32_u24_e32 v62, s9, v62
	v_add_u32_e32 v62, s7, v62
	v_lshlrev_b32_e32 v62, 1, v62
	v_lshl_add_u32 v62, v3, 4, v62
.Lht_loop:
	s_addk_i32 s3, 0x390
	s_cmpk_lt_u32 s3, 0xd00
	s_cselect_b32 s43, 1, 0
	s_cbranch_scc0 .Lht_a_last
	s_cmpk_lt_u32 s3, 0x200
	s_cbranch_scc0 .Lht2_not_out
	s_lshr_b32 s22, s3, 5
	s_and_b32 s23, s3, 31
	s_lshl_b32 s23, s23, 5
	s_mov_b32 s8, s23
	v_readlane_b32 s4, v239, 0
	v_readlane_b32 s5, v239, 1
	s_movk_i32 s25, 0x400
	s_movk_i32 s9, 0x400
	s_mov_b32 s0, 0xa00000
	s_branch .Lht2_go

; #define LAS __attribute__((address_space(3)))
; __device__ __forceinline__ void p0_transpose_item(const float* W, int ldw, int c0, int k0, bf16_t* WT, int K, int n0, const float* kscale, LAS float* scr, int lane) {
; #pragma unroll
;     for (int i = 0; i < 32; ++i) { const int kk = 2 * i + (lane >> 5); float v = 0.f;
;         if (c0 >= 0) v = __builtin_nontemporal_load(W + (size_t)(k0 + kk) * ldw + c0 + (lane & 31));
;         if (kscale) v *= kscale[k0 + kk];
;         scr[kk * 33 + (lane & 31)] = v; }
.Lht2_go:
	s_add_u32 s40, s30, s0
	s_addc_u32 s41, s31, 0
	s_lshl_b32 s42, s9, 4
	s_lshl_b32 s7, s22, 6
	s_mul_i32 s0, s7, s25
	s_add_i32 s0, s0, s8
	s_lshl_b32 s0, s0, 2
	s_add_u32 s4, s4, s0
	s_addc_u32 s5, s5, 0
	s_lshl_b32 s6, s25, 3
	v_mul_u32_u24_e32 v9, s25, v1
	v_add_lshl_u32 v9, v9, v2, 2
	global_load_dword v64, v9, s[4:5] nt
	s_add_u32 s4, s4, s6
	s_addc_u32 s5, s5, 0
	global_load_dword v65, v9, s[4:5] nt
	s_add_u32 s4, s4, s6
	s_addc_u32 s5, s5, 0
	global_load_dword v66, v9, s[4:5] nt
	s_add_u32 s4, s4, s6
	s_addc_u32 s5, s5, 0
	global_load_dword v67, v9, s[4:5] nt
	s_add_u32 s4, s4, s6
	s_addc_u32 s5, s5, 0
	global_load_dword v68, v9, s[4:5] nt
	s_add_u32 s4, s4, s6
	s_addc_u32 s5, s5, 0
	global_load_dword v69, v9, s[4:5] nt
	s_add_u32 s4, s4, s6
	s_addc_u32 s5, s5, 0
	global_load_dword v70, v9, s[4:5] nt
	s_add_u32 s4, s4, s6
	s_addc_u32 s5, s5, 0
	global_load_dword v71, v9, s[4:5] nt
	s_add_u32 s4, s4, s6
	s_addc_u32 s5, s5, 0
	global_load_dword v72, v9, s[4:5] nt
	s_add_u32 s4, s4, s6
	s_addc_u32 s5, s5, 0
	global_load_dword v73, v9, s[4:5] nt
	s_add_u32 s4, s4, s6
	s_addc_u32 s5, s5, 0
	global_load_dword v74, v9, s[4:5] nt
	s_add_u32 s4, s4, s6
	s_addc_u32 s5, s5, 0
	global_load_dword v75, v9, s[4:5] nt
	s_add_u32 s4, s4, s6
	s_addc_u32 s5, s5, 0
	global_load_dword v76, v9, s[4:5] nt
	s_add_u32 s4, s4, s6
	s_addc_u32 s5, s5, 0
	global_load_dword v77, v9, s[4:5] nt
	s_add_u32 s4, s4, s6
	s_addc_u32 s5, s5, 0
	global_load_dword v78, v9, s[4:5] nt
	s_add_u32 s4, s4, s6
	s_addc_u32 s5, s5, 0
	global_load_dword v79, v9, s[4:5] nt
	s_add_u32 s4, s4, s6
	s_addc_u32 s5, s5, 0
	global_load_dword v80, v9, s[4:5] nt
	s_add_u32 s4, s4, s6
	s_addc_u32 s5, s5, 0
	global_load_dword v81, v9, s[4:5] nt
	s_add_u32 s4, s4, s6
	s_addc_u32 s5, s5, 0
	global_load_dword v82, v9, s[4:5] nt
	s_add_u32 s4, s4, s6
	s_addc_u32 s5, s5, 0
	global_load_dword v83, v9, s[4:5] nt
	s_add_u32 s4, s4, s6
	s_addc_u32 s5, s5, 0
	global_load_dword v84, v9, s[4:5] nt
	s_add_u32 s4, s4, s6
	s_addc_u32 s5, s5, 0
	global_load_dword v85, v9, s[4:5] nt
	s_add_u32 s4, s4, s6
	s_addc_u32 s5, s5, 0
	global_load_dword v86, v9, s[4:5] nt
	s_add_u32 s4, s4, s6
	s_addc_u32 s5, s5, 0
	global_load_dword v87, v9, s[4:5] nt
	s_add_u32 s4, s4, s6
	s_addc_u32 s5, s5, 0
	global_load_dword v88, v9, s[4:5] nt
	s_add_u32 s4, s4, s6
	s_addc_u32 s5, s5, 0
	global_load_dword v89, v9, s[4:5] nt
	s_add_u32 s4, s4, s6
	s_addc_u32 s5, s5, 0
	global_load_dword v90, v9, s[4:5] nt
	s_add_u32 s4, s4, s6
	s_addc_u32 s5, s5, 0
	global_load_dword v91, v9, s[4:5] nt
	s_add_u32 s4, s4, s6
	s_addc_u32 s5, s5, 0
	global_load_dword v92, v9, s[4:5] nt
	s_add_u32 s4, s4, s6
	s_addc_u32 s5, s5, 0
	global_load_dword v93, v9, s[4:5] nt
	s_add_u32 s4, s4, s6
	s_addc_u32 s5, s5, 0
	global_load_dword v94, v9, s[4:5] nt
	s_add_u32 s4, s4, s6
	s_addc_u32 s5, s5, 0
	global_load_dword v95, v9, s[4:5] nt
	v_add_u32_e32 v63, s23, v4
	v_mul_u32_u24_e32 v63, s9, v63
	v_add_u32_e32 v63, s7, v63
	v_lshlrev_b32_e32 v63, 1, v63
	v_lshl_add_u32 v63, v3, 4, v63
	s_waitcnt vmcnt(32)
	s_branch .Lht_a_proc

; #define LAS __attribute__((address_space(3)))
; __device__ __forceinline__ unsigned cvt_pk_bf16(float lo, float hi) { unsigned r; asm("v_cvt_pk_bf16_f32 %0, %1, %2" : "=v"(r) : "v"(lo), "v"(hi)); return r; }
; #define LDS_WAIT() asm volatile("s_waitcnt lgkmcnt(0)" ::: "memory")
; __device__ __forceinline__ void p0_transpose_item(const float* W, int ldw, int c0, int k0, bf16_t* WT, int K, int n0, const float* kscale, LAS float* scr, int lane) {
;     ...
;     LDS_WAIT(); asm volatile("" ::: "memory");
;     const int c = lane & 7;
; #pragma unroll
;     for (int j = 0; j < 4; ++j) { const int n = (lane >> 3) + 8 * j; const LAS float* s = scr + (8 * c) * 33 + n;
;         u32x4 o; o.x = cvt_pk_bf16(s[0 * 33], s[1 * 33]); o.y = cvt_pk_bf16(s[2 * 33], s[3 * 33]); o.z = cvt_pk_bf16(s[4 * 33], s[5 * 33]); o.w = cvt_pk_bf16(s[6 * 33], s[7 * 33]);
;         *(u32x4*)(WT + (size_t)(n0 + n) * K + k0 + 8 * c) = o; }
;     LDS_WAIT(); asm volatile("" ::: "memory");
; }
.Lht_a_proc:
	ds_write_b32 v5, v10
	ds_write_b32 v5, v11 offset:264
	ds_write_b32 v5, v12 offset:528
	ds_write_b32 v5, v13 offset:792
	ds_write_b32 v5, v14 offset:1056
	ds_write_b32 v5, v15 offset:1320
	ds_write_b32 v5, v16 offset:1584
	ds_write_b32 v5, v17 offset:1848
	ds_write_b32 v5, v18 offset:2112
	ds_write_b32 v5, v19 offset:2376
	ds_write_b32 v5, v20 offset:2640
	ds_write_b32 v5, v21 offset:2904
	ds_write_b32 v5, v22 offset:3168
	ds_write_b32 v5, v23 offset:3432
	ds_write_b32 v5, v24 offset:3696
	ds_write_b32 v5, v25 offset:3960
	ds_write_b32 v5, v26 offset:4224
	ds_write_b32 v5, v27 offset:4488
	ds_write_b32 v5, v28 offset:4752
	ds_write_b32 v5, v29 offset:5016
	ds_write_b32 v5, v30 offset:5280
	ds_write_b32 v5, v31 offset:5544
	ds_write_b32 v5, v32 offset:5808
	ds_write_b32 v5, v33 offset:6072
	ds_write_b32 v5, v34 offset:6336
	ds_write_b32 v5, v35 offset:6600
	ds_write_b32 v5, v36 offset:6864
	ds_write_b32 v5, v37 offset:7128
	ds_write_b32 v5, v38 offset:7392
	ds_write_b32 v5, v39 offset:7656
	ds_write_b32 v5, v40 offset:7920
	ds_write_b32 v5, v41 offset:8184
	s_waitcnt lgkmcnt(0)
	ds_read_b32 v50, v8
	ds_read_b32 v51, v8 offset:132
	ds_read_b32 v52, v8 offset:264
	ds_read_b32 v53, v8 offset:396
	ds_read_b32 v54, v8 offset:528
	ds_read_b32 v55, v8 offset:660
	ds_read_b32 v56, v8 offset:792
	ds_read_b32 v57, v8 offset:924
	s_waitcnt lgkmcnt(0)
	v_cvt_pk_bf16_f32 v58, v50, v51
	v_cvt_pk_bf16_f32 v59, v52, v53
	v_cvt_pk_bf16_f32 v60, v54, v55
	v_cvt_pk_bf16_f32 v61, v56, v57
	global_store_dwordx4 v62, v[58:61], s[10:11]
	s_add_u32 s10, s10, s24
	s_addc_u32 s11, s11, 0
	s_nop 1
	ds_read_b32 v50, v8 offset:32
	ds_read_b32 v51, v8 offset:164
	ds_read_b32 v52, v8 offset:296
	ds_read_b32 v53, v8 offset:428
	ds_read_b32 v54, v8 offset:560
	ds_read_b32 v55, v8 offset:692
	ds_read_b32 v56, v8 offset:824
	ds_read_b32 v57, v8 offset:956
	s_waitcnt lgkmcnt(0)
	v_cvt_pk_bf16_f32 v58, v50, v51
	v_cvt_pk_bf16_f32 v59, v52, v53
	v_cvt_pk_bf16_f32 v60, v54, v55
	v_cvt_pk_bf16_f32 v61, v56, v57
	global_store_dwordx4 v62, v[58:61], s[10:11]
	s_add_u32 s10, s10, s24
	s_addc_u32 s11, s11, 0
	s_nop 1
	ds_read_b32 v50, v8 offset:64
	ds_read_b32 v51, v8 offset:196
	ds_read_b32 v52, v8 offset:328
	ds_read_b32 v53, v8 offset:460
	ds_read_b32 v54, v8 offset:592
	ds_read_b32 v55, v8 offset:724
	ds_read_b32 v56, v8 offset:856
	ds_read_b32 v57, v8 offset:988
	s_waitcnt lgkmcnt(0)
	v_cvt_pk_bf16_f32 v58, v50, v51
	v_cvt_pk_bf16_f32 v59, v52, v53
	v_cvt_pk_bf16_f32 v60, v54, v55
	v_cvt_pk_bf16_f32 v61, v56, v57
	global_store_dwordx4 v62, v[58:61], s[10:11]
	s_add_u32 s10, s10, s24
	s_addc_u32 s11, s11, 0
	s_nop 1
	ds_read_b32 v50, v8 offset:96
	ds_read_b32 v51, v8 offset:228
	ds_read_b32 v52, v8 offset:360
	ds_read_b32 v53, v8 offset:492
	ds_read_b32 v54, v8 offset:624
	ds_read_b32 v55, v8 offset:756
	ds_read_b32 v56, v8 offset:888
	ds_read_b32 v57, v8 offset:1020
	s_waitcnt lgkmcnt(0)
	v_cvt_pk_bf16_f32 v58, v50, v51
	v_cvt_pk_bf16_f32 v59, v52, v53
	v_cvt_pk_bf16_f32 v60, v54, v55
	v_cvt_pk_bf16_f32 v61, v56, v57
	global_store_dwordx4 v62, v[58:61], s[10:11]
	s_nop 1
	s_cmp_eq_u32 s43, 0
	s_cbranch_scc1 .Lht_exit
	s_addk_i32 s3, 0x390
	s_cmpk_lt_u32 s3, 0xd00
	s_cselect_b32 s43, 1, 0
	s_cbranch_scc0 .Lht_b_last
	s_cmpk_lt_u32 s3, 0x200
	s_cbranch_scc0 .Lht3_not_out
	s_lshr_b32 s22, s3, 5
	s_and_b32 s23, s3, 31
	s_lshl_b32 s23, s23, 5
	s_mov_b32 s8, s23
	v_readlane_b32 s4, v239, 0
	v_readlane_b32 s5, v239, 1
	s_movk_i32 s25, 0x400
	s_movk_i32 s9, 0x400
	s_mov_b32 s0, 0xa00000
	s_branch .Lht3_go

; #define LAS __attribute__((address_space(3)))
; __device__ __forceinline__ void p0_transpose_item(const float* W, int ldw, int c0, int k0, bf16_t* WT, int K, int n0, const float* kscale, LAS float* scr, int lane) {
; #pragma unroll
;     for (int i = 0; i < 32; ++i) { const int kk = 2 * i + (lane >> 5); float v = 0.f;
;         if (c0 >= 0) v = __builtin_nontemporal_load(W + (size_t)(k0 + kk) * ldw + c0 + (lane & 31));
;         if (kscale) v *= kscale[k0 + kk];
;         scr[kk * 33 + (lane & 31)] = v; }
; __global__ void __launch_bounds__(512, 2) mega_fwd(Args a) {
;     ...
;             if (r < I_OUT) { const int kb = r / 32, nb = r % 32; p0_transpose_item(w_out, 1024, nb * 32, kb * 64, Wt_out, 1024, nb * 32, nullptr, scr, lane); continue; } r -= I_OUT;
;             if (r < I_FI) { const int kb = r / 176, nb = r % 176, n0 = nb * 32, pn = n0 >> 8, bj = (n0 >> 7) & 1, rr = n0 & 127;
;                 p0_transpose_item(w_fi, 5632, bj * 2816 + 128 * pn + rr, kb * 64, Wt_fi, 1024, n0, nullptr, scr, lane); continue; } r -= I_FI;
;             if (r < I_FO) { const int kb = r / 32, nb = r % 32; p0_transpose_item(w_fo, 1024, nb * 32, kb * 64, Wt_fo, 2816, nb * 32, nullptr, scr, lane); continue; } r -= I_FO;
.Lht3_go:
	s_add_u32 s10, s30, s0
	s_addc_u32 s11, s31, 0
	s_lshl_b32 s24, s9, 4
	s_lshl_b32 s7, s22, 6
	s_mul_i32 s0, s7, s25
	s_add_i32 s0, s0, s8
	s_lshl_b32 s0, s0, 2
	s_add_u32 s4, s4, s0
	s_addc_u32 s5, s5, 0
	s_lshl_b32 s6, s25, 3
	v_mul_u32_u24_e32 v9, s25, v1
	v_add_lshl_u32 v9, v9, v2, 2
	global_load_dword v10, v9, s[4:5] nt
	s_add_u32 s4, s4, s6
	s_addc_u32 s5, s5, 0
	global_load_dword v11, v9, s[4:5] nt
	s_add_u32 s4, s4, s6
	s_addc_u32 s5, s5, 0
	global_load_dword v12, v9, s[4:5] nt
	s_add_u32 s4, s4, s6
	s_addc_u32 s5, s5, 0
	global_load_dword v13, v9, s[4:5] nt
	s_add_u32 s4, s4, s6
	s_addc_u32 s5, s5, 0
	global_load_dword v14, v9, s[4:5] nt
	s_add_u32 s4, s4, s6
	s_addc_u32 s5, s5, 0
	global_load_dword v15, v9, s[4:5] nt
	s_add_u32 s4, s4, s6
	s_addc_u32 s5, s5, 0
	global_load_dword v16, v9, s[4:5] nt
	s_add_u32 s4, s4, s6
	s_addc_u32 s5, s5, 0
	global_load_dword v17, v9, s[4:5] nt
	s_add_u32 s4, s4, s6
	s_addc_u32 s5, s5, 0
	global_load_dword v18, v9, s[4:5] nt
	s_add_u32 s4, s4, s6
	s_addc_u32 s5, s5, 0
	global_load_dword v19, v9, s[4:5] nt
	s_add_u32 s4, s4, s6
	s_addc_u32 s5, s5, 0
	global_load_dword v20, v9, s[4:5] nt
	s_add_u32 s4, s4, s6
	s_addc_u32 s5, s5, 0
	global_load_dword v21, v9, s[4:5] nt
	s_add_u32 s4, s4, s6
	s_addc_u32 s5, s5, 0
	global_load_dword v22, v9, s[4:5] nt
	s_add_u32 s4, s4, s6
	s_addc_u32 s5, s5, 0
	global_load_dword v23, v9, s[4:5] nt
	s_add_u32 s4, s4, s6
	s_addc_u32 s5, s5, 0
	global_load_dword v24, v9, s[4:5] nt
	s_add_u32 s4, s4, s6
	s_addc_u32 s5, s5, 0
	global_load_dword v25, v9, s[4:5] nt
	s_add_u32 s4, s4, s6
	s_addc_u32 s5, s5, 0
	global_load_dword v26, v9, s[4:5] nt
	s_add_u32 s4, s4, s6
	s_addc_u32 s5, s5, 0
	global_load_dword v27, v9, s[4:5] nt
	s_add_u32 s4, s4, s6
	s_addc_u32 s5, s5, 0
	global_load_dword v28, v9, s[4:5] nt
	s_add_u32 s4, s4, s6
	s_addc_u32 s5, s5, 0
	global_load_dword v29, v9, s[4:5] nt
	s_add_u32 s4, s4, s6
	s_addc_u32 s5, s5, 0
	global_load_dword v30, v9, s[4:5] nt
	s_add_u32 s4, s4, s6
	s_addc_u32 s5, s5, 0
	global_load_dword v31, v9, s[4:5] nt
	s_add_u32 s4, s4, s6
	s_addc_u32 s5, s5, 0
	global_load_dword v32, v9, s[4:5] nt
	s_add_u32 s4, s4, s6
	s_addc_u32 s5, s5, 0
	global_load_dword v33, v9, s[4:5] nt
	s_add_u32 s4, s4, s6
	s_addc_u32 s5, s5, 0
	global_load_dword v34, v9, s[4:5] nt
	s_add_u32 s4, s4, s6
	s_addc_u32 s5, s5, 0
	global_load_dword v35, v9, s[4:5] nt
	s_add_u32 s4, s4, s6
	s_addc_u32 s5, s5, 0
	global_load_dword v36, v9, s[4:5] nt
	s_add_u32 s4, s4, s6
	s_addc_u32 s5, s5, 0
	global_load_dword v37, v9, s[4:5] nt
	s_add_u32 s4, s4, s6
	s_addc_u32 s5, s5, 0
	global_load_dword v38, v9, s[4:5] nt
	s_add_u32 s4, s4, s6
	s_addc_u32 s5, s5, 0
	global_load_dword v39, v9, s[4:5] nt
	s_add_u32 s4, s4, s6
	s_addc_u32 s5, s5, 0
	global_load_dword v40, v9, s[4:5] nt
	s_add_u32 s4, s4, s6
	s_addc_u32 s5, s5, 0
	global_load_dword v41, v9, s[4:5] nt
	v_add_u32_e32 v62, s23, v4
	v_mul_u32_u24_e32 v62, s9, v62
	v_add_u32_e32 v62, s7, v62
	v_lshlrev_b32_e32 v62, 1, v62
	v_lshl_add_u32 v62, v3, 4, v62
	s_waitcnt vmcnt(32)
	s_branch .Lht_b_proc

; #define LAS __attribute__((address_space(3)))
; __device__ __forceinline__ unsigned cvt_pk_bf16(float lo, float hi) { unsigned r; asm("v_cvt_pk_bf16_f32 %0, %1, %2" : "=v"(r) : "v"(lo), "v"(hi)); return r; }
; #define LDS_WAIT() asm volatile("s_waitcnt lgkmcnt(0)" ::: "memory")
; __device__ __forceinline__ void p0_transpose_item(const float* W, int ldw, int c0, int k0, bf16_t* WT, int K, int n0, const float* kscale, LAS float* scr, int lane) {
;     ...
;     LDS_WAIT(); asm volatile("" ::: "memory");
;     const int c = lane & 7;
; #pragma unroll
;     for (int j = 0; j < 4; ++j) { const int n = (lane >> 3) + 8 * j; const LAS float* s = scr + (8 * c) * 33 + n;
;         u32x4 o; o.x = cvt_pk_bf16(s[0 * 33], s[1 * 33]); o.y = cvt_pk_bf16(s[2 * 33], s[3 * 33]); o.z = cvt_pk_bf16(s[4 * 33], s[5 * 33]); o.w = cvt_pk_bf16(s[6 * 33], s[7 * 33]);
;         *(u32x4*)(WT + (size_t)(n0 + n) * K + k0 + 8 * c) = o; }
;     LDS_WAIT(); asm volatile("" ::: "memory");
; }
.Lht_b_proc:
	ds_write_b32 v5, v64
	ds_write_b32 v5, v65 offset:264
	ds_write_b32 v5, v66 offset:528
	ds_write_b32 v5, v67 offset:792
	ds_write_b32 v5, v68 offset:1056
	ds_write_b32 v5, v69 offset:1320
	ds_write_b32 v5, v70 offset:1584
	ds_write_b32 v5, v71 offset:1848
	ds_write_b32 v5, v72 offset:2112
	ds_write_b32 v5, v73 offset:2376
	ds_write_b32 v5, v74 offset:2640
	ds_write_b32 v5, v75 offset:2904
	ds_write_b32 v5, v76 offset:3168
	ds_write_b32 v5, v77 offset:3432
	ds_write_b32 v5, v78 offset:3696
	ds_write_b32 v5, v79 offset:3960
	ds_write_b32 v5, v80 offset:4224
	ds_write_b32 v5, v81 offset:4488
	ds_write_b32 v5, v82 offset:4752
	ds_write_b32 v5, v83 offset:5016
	ds_write_b32 v5, v84 offset:5280
	ds_write_b32 v5, v85 offset:5544
	ds_write_b32 v5, v86 offset:5808
	ds_write_b32 v5, v87 offset:6072
	ds_write_b32 v5, v88 offset:6336
	ds_write_b32 v5, v89 offset:6600
	ds_write_b32 v5, v90 offset:6864
	ds_write_b32 v5, v91 offset:7128
	ds_write_b32 v5, v92 offset:7392
	ds_write_b32 v5, v93 offset:7656
	ds_write_b32 v5, v94 offset:7920
	ds_write_b32 v5, v95 offset:8184
	s_waitcnt lgkmcnt(0)
	ds_read_b32 v50, v8
	ds_read_b32 v51, v8 offset:132
	ds_read_b32 v52, v8 offset:264
	ds_read_b32 v53, v8 offset:396
	ds_read_b32 v54, v8 offset:528
	ds_read_b32 v55, v8 offset:660
	ds_read_b32 v56, v8 offset:792
	ds_read_b32 v57, v8 offset:924
	s_waitcnt lgkmcnt(0)
	v_cvt_pk_bf16_f32 v58, v50, v51
	v_cvt_pk_bf16_f32 v59, v52, v53
	v_cvt_pk_bf16_f32 v60, v54, v55
	v_cvt_pk_bf16_f32 v61, v56, v57
	global_store_dwordx4 v63, v[58:61], s[40:41]
	s_add_u32 s40, s40, s42
	s_addc_u32 s41, s41, 0
	s_nop 1
	ds_read_b32 v50, v8 offset:32
	ds_read_b32 v51, v8 offset:164
	ds_read_b32 v52, v8 offset:296
	ds_read_b32 v53, v8 offset:428
	ds_read_b32 v54, v8 offset:560
	ds_read_b32 v55, v8 offset:692
	ds_read_b32 v56, v8 offset:824
	ds_read_b32 v57, v8 offset:956
	s_waitcnt lgkmcnt(0)
	v_cvt_pk_bf16_f32 v58, v50, v51
	v_cvt_pk_bf16_f32 v59, v52, v53
	v_cvt_pk_bf16_f32 v60, v54, v55
	v_cvt_pk_bf16_f32 v61, v56, v57
	global_store_dwordx4 v63, v[58:61], s[40:41]
	s_add_u32 s40, s40, s42
	s_addc_u32 s41, s41, 0
	s_nop 1
	ds_read_b32 v50, v8 offset:64
	ds_read_b32 v51, v8 offset:196
	ds_read_b32 v52, v8 offset:328
	ds_read_b32 v53, v8 offset:460
	ds_read_b32 v54, v8 offset:592
	ds_read_b32 v55, v8 offset:724
	ds_read_b32 v56, v8 offset:856
	ds_read_b32 v57, v8 offset:988
	s_waitcnt lgkmcnt(0)
	v_cvt_pk_bf16_f32 v58, v50, v51
	v_cvt_pk_bf16_f32 v59, v52, v53
	v_cvt_pk_bf16_f32 v60, v54, v55
	v_cvt_pk_bf16_f32 v61, v56, v57
	global_store_dwordx4 v63, v[58:61], s[40:41]
	s_add_u32 s40, s40, s42
	s_addc_u32 s41, s41, 0
	s_nop 1
	ds_read_b32 v50, v8 offset:96
	ds_read_b32 v51, v8 offset:228
	ds_read_b32 v52, v8 offset:360
	ds_read_b32 v53, v8 offset:492
	ds_read_b32 v54, v8 offset:624
	ds_read_b32 v55, v8 offset:756
	ds_read_b32 v56, v8 offset:888
	ds_read_b32 v57, v8 offset:1020
	s_waitcnt lgkmcnt(0)
	v_cvt_pk_bf16_f32 v58, v50, v51
	v_cvt_pk_bf16_f32 v59, v52, v53
	v_cvt_pk_bf16_f32 v60, v54, v55
	v_cvt_pk_bf16_f32 v61, v56, v57
	global_store_dwordx4 v63, v[58:61], s[40:41]
	s_nop 1
	s_cmp_eq_u32 s43, 0
	s_cbranch_scc1 .Lht_exit
	s_branch .Lht_loop
.Lht_exit:
	v_readlane_b32 s0, v239, 8
	v_readlane_b32 s1, v239, 9
	v_readlane_b32 s3, v239, 10
	v_readlane_b32 s4, v239, 11
	v_readlane_b32 s5, v239, 12
	v_readlane_b32 s6, v239, 13
	v_readlane_b32 s7, v239, 14
	v_readlane_b32 s8, v239, 15
	v_readlane_b32 s9, v239, 16
	v_readlane_b32 s10, v239, 17
	v_readlane_b32 s11, v239, 18
	v_readlane_b32 s21, v239, 19
	v_readlane_b32 s22, v239, 20
	v_readlane_b32 s23, v239, 21
	v_readlane_b32 s24, v239, 22
	v_readlane_b32 s25, v239, 23
	v_readlane_b32 s40, v239, 24
	v_readlane_b32 s41, v239, 25
	v_readlane_b32 s42, v239, 26
	v_readlane_b32 s43, v239, 27
	v_readlane_b32 vcc_lo, v239, 30
	v_readlane_b32 vcc_hi, v239, 31

; __global__ void __launch_bounds__(512, 2) mega_fwd(Args a) {
	.amdhsa_kernel _Z8mega_fwd4Args
		.amdhsa_group_segment_fixed_size 0
		.amdhsa_private_segment_fixed_size 0
		.amdhsa_kernarg_size 464
		.amdhsa_user_sgpr_count 2
		.amdhsa_user_sgpr_dispatch_ptr 0
		.amdhsa_user_sgpr_queue_ptr 0
		.amdhsa_user_sgpr_kernarg_segment_ptr 1
		.amdhsa_user_sgpr_dispatch_id 0
		.amdhsa_user_sgpr_kernarg_preload_length 0
		.amdhsa_user_sgpr_kernarg_preload_offset 0
		.amdhsa_user_sgpr_private_segment_size 0
		.amdhsa_uses_dynamic_stack 0
		.amdhsa_enable_private_segment 0
		.amdhsa_system_sgpr_workgroup_id_x 1
		.amdhsa_system_sgpr_workgroup_id_y 0
		.amdhsa_system_sgpr_workgroup_id_z 0
		.amdhsa_system_sgpr_workgroup_info 0
		.amdhsa_system_vgpr_workitem_id 2
		.amdhsa_next_free_vgpr 240
		.amdhsa_next_free_sgpr 102
		.amdhsa_accum_offset 240
		.amdhsa_reserve_vcc 1
		.amdhsa_float_round_mode_32 0
		.amdhsa_float_round_mode_16_64 0
		.amdhsa_float_denorm_mode_32 3
		.amdhsa_float_denorm_mode_16_64 3
		.amdhsa_dx10_clamp 1
		.amdhsa_ieee_mode 1
		.amdhsa_fp16_overflow 0
		.amdhsa_tg_split 0
		.amdhsa_exception_fp_ieee_invalid_op 0
		.amdhsa_exception_fp_denorm_src 0
		.amdhsa_exception_fp_ieee_div_zero 0
		.amdhsa_exception_fp_ieee_overflow 0
		.amdhsa_exception_fp_ieee_underflow 0
		.amdhsa_exception_fp_ieee_inexact 0
		.amdhsa_exception_int_div_zero 0
	.end_amdhsa_kernel

; __global__ void __launch_bounds__(512, 2) mega_fwd(Args a) {
amdhsa.kernels:
  - .agpr_count:     0
    .args:
      - .offset:         0
        .size:           208
        .value_kind:     by_value
      - .offset:         208
        .size:           4
        .value_kind:     hidden_block_count_x
      - .offset:         212
        .size:           4
        .value_kind:     hidden_block_count_y
      - .offset:         216
        .size:           4
        .value_kind:     hidden_block_count_z
      - .offset:         220
        .size:           2
        .value_kind:     hidden_group_size_x
      - .offset:         222
        .size:           2
        .value_kind:     hidden_group_size_y
      - .offset:         224
        .size:           2
        .value_kind:     hidden_group_size_z
      - .offset:         226
        .size:           2
        .value_kind:     hidden_remainder_x
      - .offset:         228
        .size:           2
        .value_kind:     hidden_remainder_y
      - .offset:         230
        .size:           2
        .value_kind:     hidden_remainder_z
      - .offset:         248
        .size:           8
        .value_kind:     hidden_global_offset_x
      - .offset:         256
        .size:           8
        .value_kind:     hidden_global_offset_y
      - .offset:         264
        .size:           8
        .value_kind:     hidden_global_offset_z
      - .offset:         272
        .size:           2
        .value_kind:     hidden_grid_dims
      - .offset:         296
        .size:           8
        .value_kind:     hidden_multigrid_sync_arg
      - .offset:         328
        .size:           4
        .value_kind:     hidden_dynamic_lds_size
    .group_segment_fixed_size: 0
    .kernarg_segment_align: 8
    .kernarg_segment_size: 464
    .language:       OpenCL C
    .language_version:
      - 2
      - 0
    .max_flat_workgroup_size: 512
    .name:           _Z8mega_fwd4Args
    .private_segment_fixed_size: 0
    .sgpr_count:     108
    .sgpr_spill_count: 66
    .symbol:         _Z8mega_fwd4Args.kd
    .uniform_work_group_size: 1
    .uses_dynamic_stack: false
    .vgpr_count:     240
    .vgpr_spill_count: 0
    .wavefront_size: 64
